# attention tail: S5 ticket loop skipped on a 256-workgroup grid (every item is owned by a workgroup at kernel start)
# speedup vs baseline: 1.0004x; 1.0004x over previous
.LBB0_447:
	s_cmpk_eq_u32 s28, 0x100
	s_cbranch_scc1 .LBB0_516
	s_mov_b64 s[6:7], s[0:1]
	s_load_dwordx2 s[6:7], s[6:7], 0xa8
	s_mov_b64 s[22:23], s[0:1]
	s_load_dwordx8 s[8:15], s[22:23], 0x48
	s_load_dwordx2 s[42:43], s[22:23], 0xa8
	v_lshrrev_b32_e32 v65, 5, v208
	s_waitcnt lgkmcnt(0)
	s_add_u32 s24, s6, 0x44800
	v_lshlrev_b32_e32 v3, 3, v208
	v_lshlrev_b32_e32 v0, 9, v65
	s_addc_u32 s25, s7, 0
	v_bfe_u32 v2, v208, 1, 4
	v_and_b32_e32 v4, 8, v3
	v_add_u32_e32 v67, 0, v0
	s_add_u32 s38, s42, 0x3200000
	v_add_u32_e32 v0, v67, v0
	v_lshlrev_b32_e32 v1, 6, v2
	v_lshlrev_b32_e32 v5, 2, v4
	s_addc_u32 s39, s43, 0
	v_add3_u32 v69, v0, v1, v5
	v_lshlrev_b32_e32 v0, 4, v208
	s_add_u32 s40, s42, 0x300000
	v_and_b32_e32 v8, 0x1f0, v0
	v_mov_b32_e32 v9, 0
	s_addc_u32 s41, s43, 0
	v_lshl_add_u64 v[0:1], s[42:43], 0, v[8:9]
	s_mov_b64 s[42:43], 0x3e00000
	v_lshl_add_u64 v[10:11], v[0:1], 0, s[42:43]
	v_cmp_eq_u32_e32 vcc, v4, v2
	v_or_b32_e32 v0, 1, v4
	s_and_b64 s[42:43], s[4:5], vcc
	v_cmp_eq_u32_e32 vcc, v0, v2
	v_or_b32_e32 v0, 2, v4
	s_and_b64 s[44:45], s[4:5], vcc
	v_cmp_eq_u32_e32 vcc, v0, v2
	v_or_b32_e32 v0, 3, v4
	s_and_b64 s[46:47], s[4:5], vcc
	v_cmp_eq_u32_e32 vcc, v0, v2
	v_or_b32_e32 v0, 4, v4
	s_load_dwordx4 s[16:19], s[22:23], 0x68
	s_load_dwordx2 s[36:37], s[22:23], 0x78
	s_and_b64 s[48:49], s[4:5], vcc
	v_cmp_eq_u32_e32 vcc, v0, v2
	v_or_b32_e32 v0, 5, v4
	s_and_b64 s[50:51], s[4:5], vcc
	v_cmp_eq_u32_e32 vcc, v0, v2
	v_or_b32_e32 v0, 6, v4
	s_and_b64 s[52:53], s[4:5], vcc
	v_cmp_eq_u32_e32 vcc, v0, v2
	v_or_b32_e32 v0, 7, v4
	v_lshlrev_b32_e32 v64, 5, v208
	v_lshl_add_u32 v68, v4, 3, 0
	s_and_b64 s[54:55], s[4:5], vcc
	v_cmp_eq_u32_e32 vcc, v0, v2
	v_lshlrev_b32_e32 v0, 5, v210
	v_add_u32_e32 v71, 0, v3
	v_lshl_add_u32 v1, v2, 9, 0
	s_add_i32 s88, 0, 0x22048
	s_mov_b32 s58, 0x652b82fe
	s_mov_b32 s60, 0xfefa39ef
	s_mov_b32 s62, 0x3b39803f
	s_mov_b32 s64, 0x6a5dcb37
	s_mov_b32 s66, 0x6dc9c883
	s_mov_b32 s68, 0x54442d18
	s_mov_b32 s70, 0x33145c07
	s_mov_b32 s72, 0x13a86d09
	s_mov_b32 s74, 0xa8c07c9d
	s_mov_b32 s76, 0
	s_mov_b32 s78, 0
	v_cmp_gt_u32_e64 s[6:7], 64, v208
	v_lshrrev_b32_e32 v66, 1, v208
	v_and_b32_e32 v70, 0x3c0, v64
	s_and_b64 s[56:57], s[4:5], vcc
	v_add_u32_e32 v72, 0xfffffe00, v208
	v_add_u32_e32 v73, 0x2200, v71
	v_lshrrev_b32_e32 v74, 2, v208
	v_add_u32_e32 v75, 0x4200, v71
	v_add_u32_e32 v76, 0x4200, v1
	v_add_u32_e32 v77, 0x2200, v68
	s_mov_b32 s59, 0x3ff71547
	s_mov_b32 s61, 0xbfe62e42
	s_mov_b32 s63, 0xbc7abc9e
	s_mov_b32 s65, 0x3e5ade15
	s_mov_b32 s67, 0x3fe45f30
	s_mov_b32 s69, 0xbff921fb
	s_mov_b32 s71, 0xbc91a626
	s_mov_b32 s73, 0x3de61246
	s_mov_b32 s75, 0xbda93974
	s_mov_b32 s77, 0x40900000
	s_mov_b32 s79, 0xc090cc00
	v_add_u32_e32 v78, 0, v0
	s_movk_i32 s92, 0x80
	s_movk_i32 s94, 0x23f
	s_mov_b64 s[80:81], 0x800
	s_mov_b32 s95, 0xaaaaaaab
	s_movk_i32 s96, 0x300
	v_mov_b32_e32 v79, s88
	v_mov_b32_e32 v12, 0xfca7ab0c
	v_mov_b32_e32 v13, 0x3e928af3
	v_mov_b32_e32 v14, 0x623fde64
	v_mov_b32_e32 v15, 0x3ec71dee
	v_mov_b32_e32 v16, 0x7c89e6b0
	v_mov_b32_e32 v17, 0x3efa0199
	v_mov_b32_e32 v18, 0x14761f6e
	v_mov_b32_e32 v19, 0x3f2a01a0
	v_mov_b32_e32 v20, 0x1852b7b0
	v_mov_b32_e32 v21, 0x3f56c16c
	v_mov_b32_e32 v22, 0x11122322
	v_mov_b32_e32 v23, 0x3f811111
	v_mov_b32_e32 v24, 0x555502a1
	v_mov_b32_e32 v25, 0x3fa55555
	v_mov_b32_e32 v26, 0x55555511
	v_mov_b32_e32 v27, 0x3fc55555
	v_mov_b32_e32 v28, 11
	v_mov_b32_e32 v29, 0x3fe00000
	v_mov_b32_e32 v80, 0x7ff00000
	v_mov_b32_e32 v30, 0x67f544e4
	v_mov_b32_e32 v31, 0xbe5ae645
	v_mov_b32_e32 v32, 0xa556c734
	v_mov_b32_e32 v33, 0x3ec71de3
	v_mov_b32_e32 v34, 0x1a01a01a
	v_mov_b32_e32 v35, 0xbf2a01a0
	v_mov_b32_e32 v36, 0x11111111
	v_mov_b32_e32 v38, 0x55555555
	v_mov_b32_e32 v39, 0xbfc55555
	v_mov_b32_e32 v40, 0xeff8d898
	v_mov_b32_e32 v41, 0x3e21eed8
	v_mov_b32_e32 v42, 0xb7789f5c
	v_mov_b32_e32 v43, 0xbe927e4f
	v_mov_b32_e32 v45, 0x3efa01a0
	v_mov_b32_e32 v46, 0x16c16c17
	v_mov_b32_e32 v47, 0xbf56c16c
	v_mov_b32_e32 v81, 0x3ff00000
	s_branch .LBB0_450
